# attention loop: first group of P.V fragment reads issued ahead of the K/V load address block so their LDS latency overlaps it
# baseline (speedup 1.0000x reference)
;     __device__ __forceinline__ static float act(float g, float u) { return g * __builtin_amdgcn_rcpf(1.0f + __builtin_amdgcn_exp2f(g * -1.4426950408889634f)) * u; }
; __device__ __forceinline__ void finishSM(f32x16& p0, f32x16& p1, float alpha, float& l_reg, bf16x8& pa0, bf16x8& pa1, bf16x8& pa2, bf16x8& pa3) {
;     for (int r = 0; r < 16; ++r) p1[r] = __builtin_amdgcn_exp2f(p1[r]);
;     float ps = 0; for (int r = 0; r < 16; ++r) ps += p0[r]; for (int r = 0; r < 16; ++r) ps += p1[r];
;     { auto rr = __builtin_amdgcn_permlane32_swap(__float_as_uint(ps), __float_as_uint(ps), false, false);
;       ps = __uint_as_float(rr[0]) + __uint_as_float(rr[1]); }
;     l_reg = l_reg * alpha + ps;
;     ...
;     PK4(p0, 0, pa0); PK4(p0, 8, pa1); PK4(p1, 0, pa2); PK4(p1, 8, pa3);
;     ...
; }
; template <int KB, bool SK, bool NB = false>
; __device__ __forceinline__ void qkt(f32x16& p0, f32x16& p1, const char* K_lds, int r32, int hi, const bf16x8* qr, bool act, const float* g_lds, float gt) {
;     if (SK && !act) { const float NEG = -__builtin_inff();
; #pragma unroll
;         for (int r = 0; r < 16; ++r) { p0[r] = NEG; p1[r] = NEG; } return; }
;     if constexpr (NB) { p0 = f32x16{}; p1 = f32x16{}; } else
;     { const float* gl = g_lds + KB * 64 + 4 * hi;
; #pragma unroll
;       for (int g4 = 0; g4 < 4; ++g4) { const f32x4 a = *(const f32x4*)(gl + 8 * g4), b = *(const f32x4*)(gl + 32 + 8 * g4);
; #pragma unroll
;         for (int e = 0; e < 4; ++e) { p0[4 * g4 + e] = a[e]; p1[4 * g4 + e] = b[e]; } } }
;     const char* kb[4];
; #pragma unroll
;     for (int dd = 0; dd < 4; ++dd) kb[dd] = K_lds + KB * SHM_K + KSWZ(r32, (dd * 16 + hi * 8) * 2);
; #pragma unroll
;     for (int d0 = 0; d0 < 8; ++d0) { const char* a = kb[d0 & 3] + (d0 >> 2) * 128;
;         bf16x8 b0 = *reinterpret_cast<const bf16x8*>(a);
;         bf16x8 b1 = *reinterpret_cast<const bf16x8*>(a + 32 * 256);
;         p0 = __builtin_amdgcn_mfma_f32_32x32x16_bf16(b0, qr[d0], p0, 0, 0, 0);
;         p1 = __builtin_amdgcn_mfma_f32_32x32x16_bf16(b1, qr[d0], p1, 0, 0, 0); }
; }
; template <int VB, bool SK>
; __device__ __forceinline__ void pv_tile(f32x16* o, int vb0, bf16x8 pa0, bf16x8 pa1, bf16x8 pa2, bf16x8 pa3, bool act) {
;     if (SK && !act) return;
.LBB0_803:
	v_add_u32_e32 v225, 0x10900, v218
	ds_read_b128 v[64:67], v216 offset:49152
	ds_read_b128 v[84:87], v225
	ds_read_b128 v[88:91], v225 offset:32
	ds_read_b128 v[92:95], v225 offset:64
	ds_read_b128 v[96:99], v225 offset:96
	ds_read_b128 v[100:103], v216 offset:57344
	ds_read_b128 v[104:107], v216 offset:49280
	v_add_f32_e32 v177, 0, v173
	s_waitcnt lgkmcnt(2)
	v_mfma_f32_32x32x16_bf16 v[84:99], v[64:67], v[156:159], v[84:99]
	ds_read_b128 v[68:71], v225 offset:128
	ds_read_b128 v[72:75], v225 offset:160
	ds_read_b128 v[76:79], v225 offset:192
	ds_read_b128 v[80:83], v225 offset:224
	ds_read_b128 v[64:67], v216 offset:57472
	v_add_f32_e32 v177, v175, v177
	v_add_f32_e32 v177, v171, v177
	v_add_f32_e32 v177, v174, v177
	v_add_f32_e32 v177, v170, v177
	v_add_f32_e32 v177, v172, v177
	v_add_f32_e32 v177, v168, v177
	s_waitcnt lgkmcnt(1)
	v_mfma_f32_32x32x16_bf16 v[68:83], v[100:103], v[156:159], v[68:83]
	ds_read_b128 v[100:103], v217 offset:49152
	ds_read_b128 v[108:111], v217 offset:57344
	ds_read_b128 v[178:181], v217 offset:49280
	v_add_f32_e32 v177, v169, v177
	v_add_f32_e32 v177, v163, v177
	v_add_f32_e32 v177, v166, v177
	v_exp_f32_e32 v124, v124
	v_exp_f32_e32 v125, v125
	v_exp_f32_e32 v122, v122
	s_waitcnt lgkmcnt(2)
	v_mfma_f32_32x32x16_bf16 v[84:99], v[100:103], v[152:155], v[84:99]
	ds_read_b128 v[100:103], v217 offset:57472
	ds_read_b128 v[182:185], v220 offset:49152
	ds_read_b128 v[186:189], v220 offset:49280
	ds_read_b128 v[226:229], v220 offset:57344
	ds_read_b128 v[230:233], v220 offset:57472
	ds_read_b128 v[234:237], v221 offset:49152
	ds_read_b128 v[238:241], v221 offset:49280
	v_exp_f32_e32 v123, v123
	v_exp_f32_e32 v118, v118
	v_exp_f32_e32 v119, v119
	v_exp_f32_e32 v114, v114
	v_exp_f32_e32 v115, v115
	v_exp_f32_e32 v112, v112
	s_waitcnt lgkmcnt(8)
	v_mfma_f32_32x32x16_bf16 v[68:83], v[108:111], v[152:155], v[68:83]
	ds_read_b128 v[108:111], v221 offset:57344
	ds_read_b128 v[242:245], v221 offset:57472
	v_exp_f32_e32 v113, v113
	v_exp_f32_e32 v126, v126
	v_exp_f32_e32 v127, v127
	v_exp_f32_e32 v120, v120
	v_exp_f32_e32 v121, v121
	v_exp_f32_e32 v116, v116
	s_waitcnt lgkmcnt(7)
	v_mfma_f32_32x32x16_bf16 v[84:99], v[182:185], v[148:151], v[84:99]
	v_exp_f32_e32 v117, v117
	s_waitcnt lgkmcnt(5)
	v_mfma_f32_32x32x16_bf16 v[68:83], v[226:229], v[148:151], v[68:83]
	s_waitcnt lgkmcnt(3)
	v_mfma_f32_32x32x16_bf16 v[84:99], v[234:237], v[144:147], v[84:99]
	s_waitcnt lgkmcnt(1)
	v_mfma_f32_32x32x16_bf16 v[68:83], v[108:111], v[144:147], v[68:83]
	v_add_f32_e32 v108, v161, v177
	v_add_f32_e32 v108, v164, v108
	v_add_f32_e32 v108, v160, v108
	v_add_f32_e32 v108, v167, v108
	v_add_f32_e32 v108, v162, v108
	v_add_f32_e32 v108, v165, v108
	v_add_f32_e32 v108, v124, v108
	v_mfma_f32_32x32x16_bf16 v[84:99], v[104:107], v[140:143], v[84:99]
	v_add_f32_e32 v104, v125, v108
	v_add_f32_e32 v104, v122, v104
	v_add_f32_e32 v104, v123, v104
	v_add_f32_e32 v104, v118, v104
	v_add_f32_e32 v104, v119, v104
	v_add_f32_e32 v104, v114, v104
	v_add_f32_e32 v104, v115, v104
	v_mfma_f32_32x32x16_bf16 v[68:83], v[64:67], v[140:143], v[68:83]
	v_add_f32_e32 v64, v112, v104
	v_add_f32_e32 v64, v113, v64
	v_add_f32_e32 v64, v126, v64
	v_add_f32_e32 v64, v127, v64
	v_add_f32_e32 v64, v120, v64
	v_add_f32_e32 v64, v121, v64
	v_add_f32_e32 v64, v116, v64
	v_mfma_f32_32x32x16_bf16 v[84:99], v[178:181], v[136:139], v[84:99]
	v_add_f32_e32 v226, v117, v64
	v_mov_b32_e32 v227, v226
	v_cvt_pk_bf16_f32 v64, v173, v175
	v_cvt_pk_bf16_f32 v65, v171, v174
	v_cvt_pk_bf16_f32 v66, v170, v172
	v_cvt_pk_bf16_f32 v67, v168, v169
	s_nop 1
	v_permlane32_swap_b32_e32 v226, v227
	v_mfma_f32_32x32x16_bf16 v[68:83], v[100:103], v[136:139], v[68:83]
	v_cvt_pk_bf16_f32 v100, v163, v166
	v_cvt_pk_bf16_f32 v101, v161, v164
	v_cvt_pk_bf16_f32 v102, v160, v167
	v_cvt_pk_bf16_f32 v103, v162, v165
	v_cvt_pk_bf16_f32 v108, v124, v125
	v_cvt_pk_bf16_f32 v109, v122, v123
	v_cvt_pk_bf16_f32 v110, v118, v119
	v_mfma_f32_32x32x16_bf16 v[84:99], v[186:189], v[132:135], v[84:99]
	v_cvt_pk_bf16_f32 v111, v114, v115
	v_cvt_pk_bf16_f32 v104, v112, v113
	v_cvt_pk_bf16_f32 v105, v126, v127
	v_cvt_pk_bf16_f32 v106, v120, v121
	v_cvt_pk_bf16_f32 v107, v116, v117
	v_permlane32_swap_b32_e32 v64, v66
	v_mfma_f32_32x32x16_bf16 v[68:83], v[230:233], v[132:135], v[68:83]
	v_permlane32_swap_b32_e32 v65, v67
	v_permlane32_swap_b32_e32 v100, v102
	v_permlane32_swap_b32_e32 v101, v103
	v_permlane32_swap_b32_e32 v108, v110
	v_mfma_f32_32x32x16_bf16 v[84:99], v[238:241], v[128:131], v[84:99]
	v_permlane32_swap_b32_e32 v109, v111
	v_permlane32_swap_b32_e32 v104, v106
	v_permlane32_swap_b32_e32 v105, v107
	s_waitcnt lgkmcnt(0)
	v_mfma_f32_32x32x16_bf16 v[68:83], v[242:245], v[128:131], v[68:83]
	ds_read_b64_tr_b16 v[112:113], v213 offset:0
	ds_read_b64_tr_b16 v[114:115], v213 offset:0x800
	ds_read_b64_tr_b16 v[116:117], v213 offset:0x1000
	ds_read_b64_tr_b16 v[118:119], v213 offset:0x1800
	ds_read_b64_tr_b16 v[120:121], v213 offset:0x2000
	ds_read_b64_tr_b16 v[122:123], v213 offset:0x2800
	ds_read_b64_tr_b16 v[124:125], v213 offset:0x3000
	ds_read_b64_tr_b16 v[126:127], v213 offset:0x3800
	s_sub_i32 s46, s14, 64
	s_and_b64 vcc, exec, s[6:7]
	s_ashr_i32 s47, s46, 31
	s_cbranch_vccnz .LBB0_805
	v_lshl_add_u64 v[252:253], s[46:47], 2, v[200:201]
	flat_load_dword v202, v[252:253]
; __device__ __forceinline__ void mask_tile(f32x16& p0, f32x16& p1, int dq, unsigned W) {
;     const float NEG = -__builtin_inff();
; #pragma unroll
;     for (int r = 0; r < 16; ++r) {
;         const int c = (r & 3) + 8 * (r >> 2);
;         if ((unsigned)(dq - c) >= W) p0[r] = NEG;
;         if ((unsigned)(dq - c - 32) >= W) p1[r] = NEG;
;     }
; }
.LBB0_805:
	s_add_i32 s69, s14, 63
	s_lshl_b64 s[10:11], s[46:47], 8
	s_add_u32 s48, s34, s10
	s_addc_u32 s49, s35, s11
	s_add_u32 s10, s36, s10
	s_addc_u32 s11, s37, s11
	v_lshl_add_u64 v[252:253], s[10:11], 0, v[194:195]
	v_add_co_u32_e32 v254, vcc, s59, v252
	s_nop 1
	v_addc_co_u32_e32 v255, vcc, 0, v253, vcc
	flat_load_dwordx4 v[160:163], v[252:253]
	flat_load_dwordx4 v[164:167], v[254:255]
	v_lshl_add_u64 v[252:253], s[48:49], 0, v[194:195]
	v_add_co_u32_e32 v254, vcc, s59, v252
	s_nop 1
	v_addc_co_u32_e32 v255, vcc, 0, v253, vcc
	flat_load_dwordx4 v[168:171], v[252:253]
	flat_load_dwordx4 v[172:175], v[254:255]
	s_cmp_le_i32 s69, s31
	s_cselect_b64 s[10:11], -1, 0
	s_cmp_gt_i32 s14, s67
	s_cselect_b64 s[48:49], -1, 0
	s_and_b64 s[10:11], s[10:11], s[48:49]
	s_and_b64 vcc, exec, s[10:11]
	s_nop 3
	s_cbranch_vccnz .LBB0_807
	v_subrev_u32_e32 v252, 64, v224
	v_cmp_gt_u32_e32 vcc, s61, v252
	v_add_u32_e32 v252, 0xffffefa0, v224
	s_nop 0
	v_cndmask_b32_e32 v84, v203, v84, vcc
	v_cmp_lt_u32_e32 vcc, s62, v252
	v_add_u32_e32 v252, 0xffffefbf, v224
	s_nop 0
	v_cndmask_b32_e32 v68, v203, v68, vcc
	v_cmp_lt_u32_e32 vcc, s62, v252
	v_add_u32_e32 v252, 0xffffef9f, v224
	s_nop 0
	v_cndmask_b32_e32 v85, v203, v85, vcc
	v_cmp_lt_u32_e32 vcc, s62, v252
	v_add_u32_e32 v252, 0xffffefbe, v224
	s_nop 0
	v_cndmask_b32_e32 v69, v203, v69, vcc
	v_cmp_lt_u32_e32 vcc, s62, v252
	v_add_u32_e32 v252, 0xffffef9e, v224
	s_nop 0
	v_cndmask_b32_e32 v86, v203, v86, vcc
	v_cmp_lt_u32_e32 vcc, s62, v252
	v_add_u32_e32 v252, 0xffffefbd, v224
	s_nop 0
	v_cndmask_b32_e32 v70, v203, v70, vcc
	v_cmp_lt_u32_e32 vcc, s62, v252
	v_add_u32_e32 v252, 0xffffef9d, v224
	s_nop 0
	v_cndmask_b32_e32 v87, v203, v87, vcc
	v_cmp_lt_u32_e32 vcc, s62, v252
	v_add_u32_e32 v252, 0xffffefb8, v224
	s_nop 0
	v_cndmask_b32_e32 v71, v203, v71, vcc
	v_cmp_lt_u32_e32 vcc, s62, v252
	v_add_u32_e32 v252, 0xffffef98, v224
	s_nop 0
	v_cndmask_b32_e32 v88, v203, v88, vcc
	v_cmp_lt_u32_e32 vcc, s62, v252
	v_add_u32_e32 v252, 0xffffefb7, v224
	s_nop 0
	v_cndmask_b32_e32 v72, v203, v72, vcc
	v_cmp_lt_u32_e32 vcc, s62, v252
	v_add_u32_e32 v252, 0xffffef97, v224
	s_nop 0
	v_cndmask_b32_e32 v89, v203, v89, vcc
	v_cmp_lt_u32_e32 vcc, s62, v252
	v_add_u32_e32 v252, 0xffffefb6, v224
	s_nop 0
	v_cndmask_b32_e32 v73, v203, v73, vcc
	v_cmp_lt_u32_e32 vcc, s62, v252
	v_add_u32_e32 v252, 0xffffef96, v224
	s_nop 0
	v_cndmask_b32_e32 v90, v203, v90, vcc
	v_cmp_lt_u32_e32 vcc, s62, v252
	v_add_u32_e32 v252, 0xffffefb5, v224
	s_nop 0
	v_cndmask_b32_e32 v74, v203, v74, vcc
	v_cmp_lt_u32_e32 vcc, s62, v252
	v_add_u32_e32 v252, 0xffffef95, v224
	s_nop 0
	v_cndmask_b32_e32 v91, v203, v91, vcc
	v_cmp_lt_u32_e32 vcc, s62, v252
	v_add_u32_e32 v252, 0xffffefb0, v224
	s_nop 0
	v_cndmask_b32_e32 v75, v203, v75, vcc
	v_cmp_lt_u32_e32 vcc, s62, v252
	v_add_u32_e32 v252, 0xffffef90, v224
	s_nop 0
	v_cndmask_b32_e32 v92, v203, v92, vcc
	v_cmp_lt_u32_e32 vcc, s62, v252
	v_add_u32_e32 v252, 0xffffefaf, v224
	s_nop 0
	v_cndmask_b32_e32 v76, v203, v76, vcc
	v_cmp_lt_u32_e32 vcc, s62, v252
	v_add_u32_e32 v252, 0xffffef8f, v224
	s_nop 0
	v_cndmask_b32_e32 v93, v203, v93, vcc
	v_cmp_lt_u32_e32 vcc, s62, v252
	v_add_u32_e32 v252, 0xffffefae, v224
	s_nop 0
	v_cndmask_b32_e32 v77, v203, v77, vcc
	v_cmp_lt_u32_e32 vcc, s62, v252
	v_add_u32_e32 v252, 0xffffef8e, v224
	s_nop 0
	v_cndmask_b32_e32 v94, v203, v94, vcc
	v_cmp_lt_u32_e32 vcc, s62, v252
	v_add_u32_e32 v252, 0xffffefad, v224
	s_nop 0
	v_cndmask_b32_e32 v78, v203, v78, vcc
	v_cmp_lt_u32_e32 vcc, s62, v252
	v_add_u32_e32 v252, 0xffffef8d, v224
	s_nop 0
	v_cndmask_b32_e32 v95, v203, v95, vcc
	v_cmp_lt_u32_e32 vcc, s62, v252
	v_add_u32_e32 v252, 0xffffefa8, v224
	s_nop 0
	v_cndmask_b32_e32 v79, v203, v79, vcc
	v_cmp_lt_u32_e32 vcc, s62, v252
	v_add_u32_e32 v252, 0xffffef88, v224
	s_nop 0
	v_cndmask_b32_e32 v96, v203, v96, vcc
	v_cmp_lt_u32_e32 vcc, s62, v252
	v_add_u32_e32 v252, 0xffffefa7, v224
	s_nop 0
	v_cndmask_b32_e32 v80, v203, v80, vcc
	v_cmp_lt_u32_e32 vcc, s62, v252
	v_add_u32_e32 v252, 0xffffef87, v224
	s_nop 0
	v_cndmask_b32_e32 v97, v203, v97, vcc
	v_cmp_lt_u32_e32 vcc, s62, v252
	v_add_u32_e32 v252, 0xffffefa6, v224
	s_nop 0
	v_cndmask_b32_e32 v81, v203, v81, vcc
	v_cmp_lt_u32_e32 vcc, s62, v252
	v_add_u32_e32 v252, 0xffffef86, v224
	s_nop 0
	v_cndmask_b32_e32 v98, v203, v98, vcc
	v_cmp_lt_u32_e32 vcc, s62, v252
	v_add_u32_e32 v252, 0xffffefa5, v224
	s_nop 0
	v_cndmask_b32_e32 v82, v203, v82, vcc
	v_cmp_lt_u32_e32 vcc, s62, v252
	v_add_u32_e32 v252, 0xffffef85, v224
	s_nop 0
	v_cndmask_b32_e32 v99, v203, v99, vcc
	v_cmp_lt_u32_e32 vcc, s62, v252
	s_nop 1
	v_cndmask_b32_e32 v83, v203, v83, vcc
;     __device__ __forceinline__ static float act(float g, float u) { return g * __builtin_amdgcn_rcpf(1.0f + __builtin_amdgcn_exp2f(g * -1.4426950408889634f)) * u; }
; __device__ __forceinline__ void partialSM(f32x16& p0, f32x16& p1, float& m_reg, float& mn, float& alpha) {
;     float pmax = p0[0]; for (int r = 1; r < 16; ++r) pmax = fmaxf(pmax, p0[r]); for (int r = 0; r < 16; ++r) pmax = fmaxf(pmax, p1[r]);
;     { auto rr = __builtin_amdgcn_permlane32_swap(__float_as_uint(pmax), __float_as_uint(pmax), false, false);
;       pmax = fmaxf(__uint_as_float(rr[0]), __uint_as_float(rr[1])); }
;     constexpr float C2 = 1.4426950408889634f * SCALE;
;     if (__builtin_expect(__all((pmax - m_reg) * SCALE <= THR), 1)) { mn = m_reg; alpha = 1.f; }
; template <int VB, bool SK>
; __device__ __forceinline__ void pv_tile(f32x16* o, int vb0, bf16x8 pa0, bf16x8 pa1, bf16x8 pa2, bf16x8 pa3, bool act) {
;     if (SK && !act) return;
;     ...
;     PV_D0(0); PV_D0(1); PV_D0(2); PV_D0(3);
.LBB0_807:
	s_waitcnt lgkmcnt(0)
	s_nop 0
	v_mfma_f32_32x32x16_bf16 v[32:47], v[64:67], v[112:115], v[32:47]
	v_max_f32_e32 v252, v85, v85
	v_max_f32_e32 v253, v84, v84
	ds_read_b64_tr_b16 v[112:113], v213 offset:0x200
	ds_read_b64_tr_b16 v[114:115], v213 offset:0xa00
	v_mfma_f32_32x32x16_bf16 v[32:47], v[100:103], v[116:119], v[32:47]
	v_max_f32_e32 v252, v253, v252
	v_max3_f32 v252, v252, v86, v87
	ds_read_b64_tr_b16 v[116:117], v213 offset:0x1200
	ds_read_b64_tr_b16 v[118:119], v213 offset:0x1a00
	v_mfma_f32_32x32x16_bf16 v[32:47], v[108:111], v[120:123], v[32:47]
	v_max3_f32 v252, v252, v88, v89
	v_max3_f32 v252, v252, v90, v91
	ds_read_b64_tr_b16 v[120:121], v213 offset:0x2200
	ds_read_b64_tr_b16 v[122:123], v213 offset:0x2a00
	ds_read_b64_tr_b16 v[178:179], v213 offset:0x3200
	ds_read_b64_tr_b16 v[180:181], v213 offset:0x3a00
	s_waitcnt lgkmcnt(0)
	v_mfma_f32_32x32x16_bf16 v[32:47], v[104:107], v[124:127], v[32:47]
	v_max3_f32 v252, v252, v92, v93
	v_max3_f32 v252, v252, v94, v95
	v_mfma_f32_32x32x16_bf16 v[48:63], v[64:67], v[112:115], v[48:63]
	v_max3_f32 v252, v252, v96, v97
	v_max3_f32 v252, v252, v98, v99
	ds_read_b64_tr_b16 v[112:113], v213 offset:0x400
	ds_read_b64_tr_b16 v[114:115], v213 offset:0xc00
	v_mfma_f32_32x32x16_bf16 v[48:63], v[100:103], v[116:119], v[48:63]
	v_max3_f32 v252, v252, v68, v69
	v_max3_f32 v252, v252, v70, v71
	ds_read_b64_tr_b16 v[116:117], v213 offset:0x1400
	ds_read_b64_tr_b16 v[118:119], v213 offset:0x1c00
	v_mfma_f32_32x32x16_bf16 v[48:63], v[108:111], v[120:123], v[48:63]
	v_max3_f32 v252, v252, v72, v73
	v_max3_f32 v252, v252, v74, v75
	ds_read_b64_tr_b16 v[120:121], v213 offset:0x2400
	ds_read_b64_tr_b16 v[122:123], v213 offset:0x2c00
	ds_read_b64_tr_b16 v[124:125], v213 offset:0x3400
	ds_read_b64_tr_b16 v[126:127], v213 offset:0x3c00
	s_waitcnt lgkmcnt(0)
	v_mfma_f32_32x32x16_bf16 v[48:63], v[104:107], v[178:181], v[48:63]
	v_max3_f32 v252, v252, v76, v77
	v_max3_f32 v252, v252, v78, v79
	v_mfma_f32_32x32x16_bf16 v[16:31], v[64:67], v[112:115], v[16:31]
	v_max3_f32 v252, v252, v80, v81
	v_max3_f32 v252, v252, v82, v83
	ds_read_b64_tr_b16 v[112:113], v213 offset:0x600
	ds_read_b64_tr_b16 v[114:115], v213 offset:0xe00
	v_mfma_f32_32x32x16_bf16 v[16:31], v[100:103], v[116:119], v[16:31]
	v_mov_b32_e32 v253, v252
	s_nop 1
	ds_read_b64_tr_b16 v[116:117], v213 offset:0x1600
	ds_read_b64_tr_b16 v[118:119], v213 offset:0x1e00
	v_mfma_f32_32x32x16_bf16 v[16:31], v[108:111], v[120:123], v[16:31]
	v_permlane32_swap_b32_e32 v252, v253
	v_max_f32_e32 v253, v253, v253
	ds_read_b64_tr_b16 v[120:121], v213 offset:0x2600
	ds_read_b64_tr_b16 v[122:123], v213 offset:0x2e00
	ds_read_b64_tr_b16 v[178:179], v213 offset:0x3600
	ds_read_b64_tr_b16 v[180:181], v213 offset:0x3e00
	s_waitcnt lgkmcnt(0)
	v_mfma_f32_32x32x16_bf16 v[16:31], v[104:107], v[124:127], v[16:31]
	v_max_f32_e32 v252, v252, v252
	v_max_f32_e32 v252, v252, v253
	v_mfma_f32_32x32x16_bf16 v[0:15], v[64:67], v[112:115], v[0:15]
	v_sub_f32_e32 v253, v252, v176
	v_mul_f32_e32 v253, 0x3db504f3, v253
	v_mfma_f32_32x32x16_bf16 v[0:15], v[100:103], v[116:119], v[0:15]
	v_cmp_ge_f32_e32 vcc, s63, v253
	v_mfma_f32_32x32x16_bf16 v[0:15], v[108:111], v[120:123], v[0:15]
	v_mfma_f32_32x32x16_bf16 v[0:15], v[104:107], v[178:181], v[0:15]
	v_mov_b32_e32 v64, v252
	s_waitcnt lgkmcnt(0)
	s_barrier
	s_waitcnt vmcnt(0)
	s_cmp_eq_u64 vcc, exec
	s_cselect_b64 s[10:11], -1, 0
	s_and_b64 vcc, exec, s[6:7]
	s_waitcnt vmcnt(0)
	ds_write_b128 v199, v[160:163]
	ds_write_b128 v215, v[164:167]
	s_cbranch_vccnz .LBB0_809
	v_xor_b32_e32 v65, 0x80000000, v202
	ds_write_b32 v212, v65

; __device__ __forceinline__ void partialSM(f32x16& p0, f32x16& p1, float& m_reg, float& mn, float& alpha) {
;     ...
;     if (__builtin_expect(__all((pmax - m_reg) * SCALE <= THR), 1)) { mn = m_reg; alpha = 1.f; }
;     else { mn = fmaxf(m_reg, pmax); alpha = __builtin_amdgcn_exp2f((m_reg - mn) * C2); m_reg = mn; }
;     const float mnL = -mn * C2;
;     for (int r = 0; r < 16; ++r) p0[r] = fmaf(p0[r], C2, mnL); for (int r = 0; r < 16; ++r) p1[r] = fmaf(p1[r], C2, mnL);
;     for (int r = 0; r < 16; ++r) p0[r] = __builtin_amdgcn_exp2f(p0[r]);
.LBB0_813:
	v_cndmask_b32_e64 v229, v64, v176, s[10:11]
	v_mul_f32_e32 v176, 0xbe0293ee, v229
	v_fmamk_f32 v64, v84, 0x3e0293ee, v176
	v_fmamk_f32 v65, v85, 0x3e0293ee, v176
	v_fmamk_f32 v66, v86, 0x3e0293ee, v176
	v_fmamk_f32 v67, v87, 0x3e0293ee, v176
	v_fmamk_f32 v100, v88, 0x3e0293ee, v176
	v_fmamk_f32 v101, v89, 0x3e0293ee, v176
	v_fmamk_f32 v102, v90, 0x3e0293ee, v176
	v_fmamk_f32 v103, v91, 0x3e0293ee, v176
	v_fmamk_f32 v104, v92, 0x3e0293ee, v176
	v_fmamk_f32 v105, v93, 0x3e0293ee, v176
	v_fmamk_f32 v106, v94, 0x3e0293ee, v176
	v_fmamk_f32 v107, v95, 0x3e0293ee, v176
	v_fmamk_f32 v96, v96, 0x3e0293ee, v176
	v_fmamk_f32 v97, v97, 0x3e0293ee, v176
	v_fmamk_f32 v98, v98, 0x3e0293ee, v176
	v_fmamk_f32 v99, v99, 0x3e0293ee, v176
	v_fmamk_f32 v84, v68, 0x3e0293ee, v176
	v_fmamk_f32 v93, v69, 0x3e0293ee, v176
	v_fmamk_f32 v94, v70, 0x3e0293ee, v176
	v_fmamk_f32 v95, v71, 0x3e0293ee, v176
	v_fmamk_f32 v177, v72, 0x3e0293ee, v176
	v_fmamk_f32 v85, v73, 0x3e0293ee, v176
	v_fmamk_f32 v86, v74, 0x3e0293ee, v176
	v_fmamk_f32 v87, v75, 0x3e0293ee, v176
	v_fmamk_f32 v88, v76, 0x3e0293ee, v176
	v_fmamk_f32 v89, v77, 0x3e0293ee, v176
	v_fmamk_f32 v90, v78, 0x3e0293ee, v176
	v_fmamk_f32 v91, v79, 0x3e0293ee, v176
	v_exp_f32_e32 v64, v64
	v_exp_f32_e32 v65, v65
	v_exp_f32_e32 v66, v66
	v_exp_f32_e32 v67, v67
	v_exp_f32_e32 v68, v100
	v_exp_f32_e32 v69, v101
	v_exp_f32_e32 v70, v102
	v_exp_f32_e32 v71, v103
	v_exp_f32_e32 v72, v104
	v_exp_f32_e32 v73, v105
	v_exp_f32_e32 v74, v106
	v_exp_f32_e32 v75, v107
	v_exp_f32_e32 v76, v96
	v_exp_f32_e32 v77, v97
	v_exp_f32_e32 v78, v98
	v_exp_f32_e32 v79, v99
	v_fmamk_f32 v92, v80, 0x3e0293ee, v176
	v_fmamk_f32 v178, v81, 0x3e0293ee, v176
	v_fmamk_f32 v179, v82, 0x3e0293ee, v176
	v_fmac_f32_e32 v176, 0x3e0293ee, v83
	s_waitcnt lgkmcnt(0)
	s_barrier
;     __device__ __forceinline__ static float act(float g, float u) { return g * __builtin_amdgcn_rcpf(1.0f + __builtin_amdgcn_exp2f(g * -1.4426950408889634f)) * u; }
; __device__ __forceinline__ void finishSM(f32x16& p0, f32x16& p1, float alpha, float& l_reg, bf16x8& pa0, bf16x8& pa1, bf16x8& pa2, bf16x8& pa3) {
;     for (int r = 0; r < 16; ++r) p1[r] = __builtin_amdgcn_exp2f(p1[r]);
;     float ps = 0; for (int r = 0; r < 16; ++r) ps += p0[r]; for (int r = 0; r < 16; ++r) ps += p1[r];
;     { auto rr = __builtin_amdgcn_permlane32_swap(__float_as_uint(ps), __float_as_uint(ps), false, false);
;       ps = __uint_as_float(rr[0]) + __uint_as_float(rr[1]); }
;     l_reg = l_reg * alpha + ps;
;     ...
;     PK4(p0, 0, pa0); PK4(p0, 8, pa1); PK4(p1, 0, pa2); PK4(p1, 8, pa3);
;     ...
; }
; template <int KB, bool SK, bool NB = false>
; __device__ __forceinline__ void qkt(f32x16& p0, f32x16& p1, const char* K_lds, int r32, int hi, const bf16x8* qr, bool act, const float* g_lds, float gt) {
;     if (SK && !act) { const float NEG = -__builtin_inff();
; #pragma unroll
;         for (int r = 0; r < 16; ++r) { p0[r] = NEG; p1[r] = NEG; } return; }
;     if constexpr (NB) { p0 = f32x16{}; p1 = f32x16{}; } else
;     { const float* gl = g_lds + KB * 64 + 4 * hi;
; #pragma unroll
;       for (int g4 = 0; g4 < 4; ++g4) { const f32x4 a = *(const f32x4*)(gl + 8 * g4), b = *(const f32x4*)(gl + 32 + 8 * g4);
; #pragma unroll
;         for (int e = 0; e < 4; ++e) { p0[4 * g4 + e] = a[e]; p1[4 * g4 + e] = b[e]; } } }
;     const char* kb[4];
; #pragma unroll
;     for (int dd = 0; dd < 4; ++dd) kb[dd] = K_lds + KB * SHM_K + KSWZ(r32, (dd * 16 + hi * 8) * 2);
; #pragma unroll
;     for (int d0 = 0; d0 < 8; ++d0) { const char* a = kb[d0 & 3] + (d0 >> 2) * 128;
;         bf16x8 b0 = *reinterpret_cast<const bf16x8*>(a);
;         bf16x8 b1 = *reinterpret_cast<const bf16x8*>(a + 32 * 256);
;         p0 = __builtin_amdgcn_mfma_f32_32x32x16_bf16(b0, qr[d0], p0, 0, 0, 0);
;         p1 = __builtin_amdgcn_mfma_f32_32x32x16_bf16(b1, qr[d0], p1, 0, 0, 0); }
; }
; template <int VB, bool SK>
; __device__ __forceinline__ void pv_tile(f32x16* o, int vb0, bf16x8 pa0, bf16x8 pa1, bf16x8 pa2, bf16x8 pa3, bool act) {
;     if (SK && !act) return;
	ds_read_b128 v[112:115], v219
	ds_read_b128 v[116:119], v219 offset:32
	ds_read_b128 v[96:99], v219 offset:128
	ds_read_b128 v[100:103], v219 offset:160
	ds_read_b128 v[120:123], v219 offset:64
	ds_read_b128 v[104:107], v219 offset:192
	ds_read_b128 v[124:127], v219 offset:96
	ds_read_b128 v[108:111], v219 offset:224
	ds_read_b128 v[80:83], v216 offset:32768
	ds_read_b128 v[180:183], v216 offset:40960
	v_exp_f32_e32 v85, v85
	v_exp_f32_e32 v86, v86
	v_exp_f32_e32 v87, v87
	s_waitcnt lgkmcnt(1)
	v_mfma_f32_32x32x16_bf16 v[112:127], v[80:83], v[156:159], v[112:127]
	v_exp_f32_e32 v88, v88
	v_exp_f32_e32 v89, v89
	v_exp_f32_e32 v90, v90
	v_exp_f32_e32 v91, v91
	v_exp_f32_e32 v92, v92
	s_waitcnt lgkmcnt(0)
	v_mfma_f32_32x32x16_bf16 v[96:111], v[180:183], v[156:159], v[96:111]
	ds_read_b128 v[80:83], v217 offset:32768
	ds_read_b128 v[180:183], v217 offset:40960
	s_waitcnt lgkmcnt(1)
	v_mfma_f32_32x32x16_bf16 v[112:127], v[80:83], v[152:155], v[112:127]
	s_waitcnt lgkmcnt(0)
	v_mfma_f32_32x32x16_bf16 v[96:111], v[180:183], v[152:155], v[96:111]
	ds_read_b128 v[80:83], v220 offset:32768
	ds_read_b128 v[180:183], v220 offset:40960
	s_waitcnt lgkmcnt(1)
	v_mfma_f32_32x32x16_bf16 v[112:127], v[80:83], v[148:151], v[112:127]
	s_waitcnt lgkmcnt(0)
	v_mfma_f32_32x32x16_bf16 v[96:111], v[180:183], v[148:151], v[96:111]
	ds_read_b128 v[80:83], v221 offset:32768
	ds_read_b128 v[180:183], v221 offset:40960
	s_waitcnt lgkmcnt(1)
	v_mfma_f32_32x32x16_bf16 v[112:127], v[80:83], v[144:147], v[112:127]
	s_waitcnt lgkmcnt(0)
	v_mfma_f32_32x32x16_bf16 v[96:111], v[180:183], v[144:147], v[96:111]
	ds_read_b128 v[80:83], v216 offset:32896
	ds_read_b128 v[180:183], v216 offset:41088
	s_waitcnt lgkmcnt(1)
	v_mfma_f32_32x32x16_bf16 v[112:127], v[80:83], v[140:143], v[112:127]
	s_waitcnt lgkmcnt(0)
	v_mfma_f32_32x32x16_bf16 v[96:111], v[180:183], v[140:143], v[96:111]
	ds_read_b128 v[80:83], v217 offset:32896
	ds_read_b128 v[180:183], v217 offset:41088
	s_waitcnt lgkmcnt(1)
	v_mfma_f32_32x32x16_bf16 v[112:127], v[80:83], v[136:139], v[112:127]
	s_waitcnt lgkmcnt(0)
	v_mfma_f32_32x32x16_bf16 v[96:111], v[180:183], v[136:139], v[96:111]
	ds_read_b128 v[80:83], v220 offset:32896
	ds_read_b128 v[180:183], v220 offset:41088
	s_waitcnt lgkmcnt(1)
	v_mfma_f32_32x32x16_bf16 v[112:127], v[80:83], v[132:135], v[112:127]
	s_waitcnt lgkmcnt(0)
	v_mfma_f32_32x32x16_bf16 v[96:111], v[180:183], v[132:135], v[96:111]
	ds_read_b128 v[80:83], v221 offset:32896
	ds_read_b128 v[180:183], v221 offset:41088
	s_waitcnt lgkmcnt(1)
	v_mfma_f32_32x32x16_bf16 v[112:127], v[80:83], v[128:131], v[112:127]
	v_exp_f32_e32 v83, v95
	v_exp_f32_e32 v95, v176
	v_add_f32_e32 v176, 0, v64
	v_add_f32_e32 v176, v65, v176
	v_add_f32_e32 v176, v66, v176
	v_add_f32_e32 v176, v67, v176
	v_add_f32_e32 v176, v68, v176
	v_add_f32_e32 v176, v69, v176
	v_add_f32_e32 v176, v70, v176
	v_add_f32_e32 v176, v71, v176
	v_add_f32_e32 v176, v72, v176
	v_add_f32_e32 v176, v73, v176
	v_add_f32_e32 v176, v74, v176
	v_add_f32_e32 v176, v75, v176
	v_exp_f32_e32 v80, v84
	v_add_f32_e32 v176, v76, v176
	v_exp_f32_e32 v81, v93
	v_add_f32_e32 v176, v77, v176
	v_exp_f32_e32 v82, v94
	v_add_f32_e32 v176, v78, v176
	v_add_f32_e32 v176, v79, v176
	v_exp_f32_e32 v84, v177
	v_add_f32_e32 v176, v80, v176
	v_add_f32_e32 v176, v81, v176
	v_add_f32_e32 v176, v82, v176
	v_add_f32_e32 v176, v83, v176
	v_add_f32_e32 v176, v84, v176
	v_add_f32_e32 v176, v85, v176
	v_add_f32_e32 v176, v86, v176
	v_add_f32_e32 v176, v87, v176
	v_add_f32_e32 v176, v88, v176
	v_exp_f32_e32 v93, v178
	v_add_f32_e32 v176, v89, v176
	s_waitcnt lgkmcnt(0)
	v_mfma_f32_32x32x16_bf16 v[96:111], v[180:183], v[128:131], v[96:111]
	v_exp_f32_e32 v94, v179
	v_add_f32_e32 v176, v90, v176
	v_add_f32_e32 v176, v91, v176
	v_add_f32_e32 v176, v92, v176
	v_add_f32_e32 v176, v93, v176
	v_add_f32_e32 v176, v94, v176
	v_add_f32_e32 v230, v95, v176
	v_mov_b32_e32 v231, v230
	v_cvt_pk_bf16_f32 v176, v64, v65
	v_cvt_pk_bf16_f32 v177, v66, v67
	v_cvt_pk_bf16_f32 v178, v68, v69
	v_cvt_pk_bf16_f32 v179, v70, v71
	v_cvt_pk_bf16_f32 v180, v72, v73
	v_cvt_pk_bf16_f32 v181, v74, v75
	v_cvt_pk_bf16_f32 v182, v76, v77
	v_cvt_pk_bf16_f32 v183, v78, v79
	v_cvt_pk_bf16_f32 v184, v80, v81
	v_cvt_pk_bf16_f32 v185, v82, v83
	v_cvt_pk_bf16_f32 v186, v84, v85
	v_cvt_pk_bf16_f32 v187, v86, v87
	v_cvt_pk_bf16_f32 v188, v88, v89
	v_cvt_pk_bf16_f32 v189, v90, v91
	v_cvt_pk_bf16_f32 v190, v92, v93
	v_cvt_pk_bf16_f32 v191, v94, v95
	s_nop 1
	v_permlane32_swap_b32_e32 v230, v231
	v_permlane32_swap_b32_e32 v176, v178
	v_permlane32_swap_b32_e32 v177, v179
	v_permlane32_swap_b32_e32 v180, v182
	v_permlane32_swap_b32_e32 v181, v183
	v_permlane32_swap_b32_e32 v184, v186
	v_permlane32_swap_b32_e32 v185, v187
	v_permlane32_swap_b32_e32 v188, v190
	v_permlane32_swap_b32_e32 v189, v191
	ds_read_b64_tr_b16 v[232:233], v213 offset:0x4000
	ds_read_b64_tr_b16 v[234:235], v213 offset:0x4800
	ds_read_b64_tr_b16 v[236:237], v213 offset:0x5000
	ds_read_b64_tr_b16 v[238:239], v213 offset:0x5800
	ds_read_b64_tr_b16 v[240:241], v213 offset:0x6000
	ds_read_b64_tr_b16 v[242:243], v213 offset:0x6800
	ds_read_b64_tr_b16 v[244:245], v213 offset:0x7000
	ds_read_b64_tr_b16 v[246:247], v213 offset:0x7800
	s_add_i32 s10, s68, 1
	s_cmp_lt_u32 s10, s66
	s_cselect_b64 s[48:49], -1, 0
	s_cmp_ge_u32 s10, s66
	s_cbranch_scc1 .LBB0_817
	s_add_i32 s10, s14, 0xffffff80
	s_and_b64 vcc, exec, s[6:7]
	s_ashr_i32 s11, s10, 31
	s_cbranch_vccnz .LBB0_816
	v_lshl_add_u64 v[160:161], s[10:11], 2, v[200:201]
	flat_load_dword v202, v[160:161]

;     __device__ __forceinline__ static float act(float g, float u) { return g * __builtin_amdgcn_rcpf(1.0f + __builtin_amdgcn_exp2f(g * -1.4426950408889634f)) * u; }
; __device__ __forceinline__ void partialSM(f32x16& p0, f32x16& p1, float& m_reg, float& mn, float& alpha) {
;     float pmax = p0[0]; for (int r = 1; r < 16; ++r) pmax = fmaxf(pmax, p0[r]); for (int r = 0; r < 16; ++r) pmax = fmaxf(pmax, p1[r]);
;     { auto rr = __builtin_amdgcn_permlane32_swap(__float_as_uint(pmax), __float_as_uint(pmax), false, false);
;       pmax = fmaxf(__uint_as_float(rr[0]), __uint_as_float(rr[1])); }
;     constexpr float C2 = 1.4426950408889634f * SCALE;
;     if (__builtin_expect(__all((pmax - m_reg) * SCALE <= THR), 1)) { mn = m_reg; alpha = 1.f; }
; template <int VB, bool SK>
; __device__ __forceinline__ void pv_tile(f32x16* o, int vb0, bf16x8 pa0, bf16x8 pa1, bf16x8 pa2, bf16x8 pa3, bool act) {
;     if (SK && !act) return;
;     ...
;     PV_D0(0); PV_D0(1); PV_D0(2); PV_D0(3);
.LBB0_819:
	s_waitcnt lgkmcnt(0)
	v_mfma_f32_32x32x16_bf16 v[32:47], v[176:179], v[232:235], v[32:47]
	v_max_f32_e32 v252, v113, v113
	v_max_f32_e32 v253, v112, v112
	ds_read_b64_tr_b16 v[232:233], v213 offset:0x4200
	ds_read_b64_tr_b16 v[234:235], v213 offset:0x4a00
	v_mfma_f32_32x32x16_bf16 v[32:47], v[180:183], v[236:239], v[32:47]
	v_max_f32_e32 v252, v253, v252
	v_max3_f32 v252, v252, v114, v115
	ds_read_b64_tr_b16 v[236:237], v213 offset:0x5200
	ds_read_b64_tr_b16 v[238:239], v213 offset:0x5a00
	v_mfma_f32_32x32x16_bf16 v[32:47], v[184:187], v[240:243], v[32:47]
	v_max3_f32 v252, v252, v116, v117
	v_max3_f32 v252, v252, v118, v119
	ds_read_b64_tr_b16 v[240:241], v213 offset:0x6200
	ds_read_b64_tr_b16 v[242:243], v213 offset:0x6a00
	ds_read_b64_tr_b16 v[248:249], v213 offset:0x7200
	ds_read_b64_tr_b16 v[250:251], v213 offset:0x7a00
	s_waitcnt lgkmcnt(0)
	v_mfma_f32_32x32x16_bf16 v[32:47], v[188:191], v[244:247], v[32:47]
	v_max3_f32 v252, v252, v120, v121
	v_max3_f32 v252, v252, v122, v123
	v_mfma_f32_32x32x16_bf16 v[48:63], v[176:179], v[232:235], v[48:63]
	v_max3_f32 v252, v252, v124, v125
	v_max3_f32 v252, v252, v126, v127
	ds_read_b64_tr_b16 v[232:233], v213 offset:0x4400
	ds_read_b64_tr_b16 v[234:235], v213 offset:0x4c00
	v_mfma_f32_32x32x16_bf16 v[48:63], v[180:183], v[236:239], v[48:63]
	v_max3_f32 v252, v252, v96, v97
	v_max3_f32 v252, v252, v98, v99
	ds_read_b64_tr_b16 v[236:237], v213 offset:0x5400
	ds_read_b64_tr_b16 v[238:239], v213 offset:0x5c00
	v_mfma_f32_32x32x16_bf16 v[48:63], v[184:187], v[240:243], v[48:63]
	v_max3_f32 v252, v252, v100, v101
	v_max3_f32 v252, v252, v102, v103
	ds_read_b64_tr_b16 v[240:241], v213 offset:0x6400
	ds_read_b64_tr_b16 v[242:243], v213 offset:0x6c00
	ds_read_b64_tr_b16 v[244:245], v213 offset:0x7400
	ds_read_b64_tr_b16 v[246:247], v213 offset:0x7c00
	s_waitcnt lgkmcnt(0)
	v_mfma_f32_32x32x16_bf16 v[48:63], v[188:191], v[248:251], v[48:63]
	v_max3_f32 v252, v252, v104, v105
	v_max3_f32 v252, v252, v106, v107
	v_mfma_f32_32x32x16_bf16 v[16:31], v[176:179], v[232:235], v[16:31]
	v_max3_f32 v252, v252, v108, v109
	v_max3_f32 v252, v252, v110, v111
	ds_read_b64_tr_b16 v[232:233], v213 offset:0x4600
	ds_read_b64_tr_b16 v[234:235], v213 offset:0x4e00
	v_mfma_f32_32x32x16_bf16 v[16:31], v[180:183], v[236:239], v[16:31]
	v_mov_b32_e32 v253, v252
	s_nop 1
	ds_read_b64_tr_b16 v[236:237], v213 offset:0x5600
	ds_read_b64_tr_b16 v[238:239], v213 offset:0x5e00
	v_mfma_f32_32x32x16_bf16 v[16:31], v[184:187], v[240:243], v[16:31]
	v_permlane32_swap_b32_e32 v252, v253
	v_max_f32_e32 v253, v253, v253
	ds_read_b64_tr_b16 v[240:241], v213 offset:0x6600
	ds_read_b64_tr_b16 v[242:243], v213 offset:0x6e00
	ds_read_b64_tr_b16 v[248:249], v213 offset:0x7600
	ds_read_b64_tr_b16 v[250:251], v213 offset:0x7e00
	s_waitcnt lgkmcnt(0)
	v_mfma_f32_32x32x16_bf16 v[16:31], v[188:191], v[244:247], v[16:31]
	v_max_f32_e32 v252, v252, v252
	v_max_f32_e32 v252, v252, v253
	v_mfma_f32_32x32x16_bf16 v[0:15], v[176:179], v[232:235], v[0:15]
	v_sub_f32_e32 v253, v252, v229
	v_mul_f32_e32 v253, 0x3db504f3, v253
	v_mfma_f32_32x32x16_bf16 v[0:15], v[180:183], v[236:239], v[0:15]
	v_cmp_ge_f32_e32 vcc, s63, v253
	v_mfma_f32_32x32x16_bf16 v[0:15], v[184:187], v[240:243], v[0:15]
	v_mfma_f32_32x32x16_bf16 v[0:15], v[188:191], v[248:251], v[0:15]
	v_mov_b32_e32 v176, v252
	s_cmp_eq_u64 vcc, exec
	s_cselect_b64 s[10:11], -1, 0
	s_andn2_b64 vcc, exec, s[48:49]
	s_waitcnt lgkmcnt(0)
	s_barrier
	s_cbranch_vccnz .LBB0_823
	s_waitcnt vmcnt(0)
	s_and_b64 vcc, exec, s[6:7]
	s_waitcnt vmcnt(0)
	ds_write_b128 v199, v[160:163] offset:16384
	ds_write_b128 v215, v[164:167] offset:16384
	s_cbranch_vccnz .LBB0_822
	v_xor_b32_e32 v160, 0x80000000, v202
	ds_write_b32 v212, v160 offset:256
